# P8 K-loop restructured too (second A-fragment set in the epilogue row-offset registers, recomputed at epilogue head)
# baseline (speedup 1.0000x reference)
.LBB0_894:
	s_add_u32 s76, s50, 0x114000
	s_addc_u32 s77, s51, 0
	s_and_b32 s18, s12, 3
	s_lshl_b32 s15, s3, 13
	s_lshl_b32 s22, s18, 9
	s_add_u32 s12, s40, 0x88800
	s_addc_u32 s13, s41, 0
	s_add_i32 m0, s33, 0x18000
	v_lshl_add_u64 v[6:7], s[12:13], 0, v[138:139]
	s_waitcnt vmcnt(0)
	s_barrier
	global_load_lds_dwordx4 v[6:7], off
	v_lshl_add_u64 v[6:7], s[12:13], 0, v[142:143]
	s_add_i32 m0, s33, 0x1a000
	s_mov_b64 s[12:13], 0x80
	s_add_i32 s78, s33, 0x8000
	s_add_i32 s79, s33, 0xa000
	global_load_lds_dwordx4 v[6:7], off
	v_lshl_add_u64 v[2:3], v[2:3], 0, s[12:13]
	s_mov_b32 m0, s78
	s_add_u32 s20, s40, 0x89000
	global_load_lds_dwordx4 v[2:3], off
	v_lshl_add_u64 v[2:3], v[4:5], 0, s[12:13]
	s_mov_b32 m0, s79
	s_addc_u32 s21, s41, 0
	global_load_lds_dwordx4 v[2:3], off
	s_add_i32 m0, s33, 0x1c000
	v_lshl_add_u64 v[2:3], s[20:21], 0, v[138:139]
	global_load_lds_dwordx4 v[2:3], off
	v_lshl_add_u64 v[2:3], s[20:21], 0, v[142:143]
	s_add_i32 m0, s33, 0x1e000
	v_and_b32_e32 v1, 15, v0
	global_load_lds_dwordx4 v[2:3], off
	v_bfe_u32 v2, v0, 4, 2
	v_lshlrev_b32_e32 v3, 4, v2
	v_lshl_or_b32 v3, v1, 6, v3
	v_lshlrev_b32_e32 v4, 2, v0
	v_lshlrev_b32_e32 v2, 11, v2
	v_lshlrev_b32_e32 v1, 4, v1
	v_and_b32_e32 v4, 32, v4
	v_or3_b32 v182, s22, v1, v2
	s_cmpk_lt_u32 s14, 0x100
	v_and_b32_e32 v1, 3, v0
	v_and_b32_e32 v2, 60, v0
	v_bfe_u32 v0, v0, 2, 4
	v_readlane_b32 s20, v249, 2
	v_bitop3_b32 v16, v3, s15, v4 bitop3:0xde
	s_cselect_b64 s[14:15], -1, 0
	v_lshl_or_b32 v0, s3, 6, v0
	s_lshl_b32 s3, s20, 2
	s_waitcnt vmcnt(6)
	v_lshlrev_b32_e32 v3, 3, v1
	v_lshl_or_b32 v184, v1, 6, v2
	v_or_b32_e32 v2, 16, v0
	v_or_b32_e32 v4, 32, v0
	v_or_b32_e32 v6, 48, v0
	v_add_u32_e32 v8, 0x80, v0
	v_add_u32_e32 v10, 0x90, v0
	v_add_u32_e32 v12, 0xa0, v0
	v_add_u32_e32 v14, 0xb0, v0
	s_and_b32 s84, s3, 12
	s_ashr_i32 s3, s20, 6
	v_lshl_or_b32 v183, s18, 5, v3
	v_ashrrev_i32_e32 v1, 31, v0
	v_ashrrev_i32_e32 v3, 31, v2
	v_ashrrev_i32_e32 v5, 31, v4
	v_ashrrev_i32_e32 v7, 31, v6
	v_ashrrev_i32_e32 v9, 31, v8
	v_ashrrev_i32_e32 v11, 31, v10
	v_ashrrev_i32_e32 v13, 31, v12
	v_ashrrev_i32_e32 v15, 31, v14
	v_readlane_b32 s21, v249, 3
	s_add_i32 s84, s84, s3
	s_movk_i32 s3, 0x2080
	v_lshlrev_b64 v[144:145], 14, v[0:1]
	v_lshlrev_b64 v[146:147], 14, v[2:3]
	v_lshlrev_b64 v[148:149], 14, v[4:5]
	v_lshlrev_b64 v[150:151], 14, v[6:7]
	v_lshlrev_b64 v[152:153], 14, v[8:9]
	v_lshlrev_b64 v[154:155], 14, v[10:11]
	v_lshlrev_b64 v[156:157], 14, v[12:13]
	v_lshlrev_b64 v[158:159], 14, v[14:15]
	s_ashr_i32 s80, s92, 31
	s_ashr_i32 s81, s20, 31
	s_and_b32 s82, s20, 4
	s_bfe_u32 s83, s20, 0x30003
	v_mad_i64_i32 v[160:161], s[20:21], v0, s3, 0
	v_mad_i64_i32 v[162:163], s[20:21], v2, s3, 0
	v_mad_i64_i32 v[164:165], s[20:21], v4, s3, 0
	v_mad_i64_i32 v[166:167], s[20:21], v6, s3, 0
	v_mad_i64_i32 v[168:169], s[20:21], v8, s3, 0
	v_mad_i64_i32 v[170:171], s[20:21], v10, s3, 0
	v_mad_i64_i32 v[172:173], s[20:21], v12, s3, 0
	v_mad_i64_i32 v[174:175], s[20:21], v14, s3, 0
	v_mov_b32_e32 v186, s2
	s_movk_i32 s18, 0x61
	s_add_i32 s36, 0, 0x10000
	s_add_i32 s37, 0, 0x14000
	v_add_u32_e32 v185, 0, v16
	v_mov_b64_e32 v[176:177], 0x2ff
	s_barrier
	s_branch .LBB0_897

.LBB0_933:
	s_lshl_b32 s2, s88, 7
	s_add_u32 s26, s34, s2
	s_addc_u32 s27, s35, 0
	s_add_u32 s98, s26, 0x80
	s_addc_u32 s99, s27, 0
	s_add_u32 s46, s26, 0x100
	s_addc_u32 s47, s27, 0
	s_and_b64 s[2:3], s[44:45], exec
	s_cselect_b32 s51, s47, s23
	s_cselect_b32 s50, s46, s22
	s_mul_i32 s2, s88, 0x88800
	s_add_u32 s2, s40, s2
	s_addc_u32 s3, s41, 0
	s_add_u32 s100, s2, 0x88800
	s_addc_u32 s101, s3, 0
	s_add_u32 s46, s2, 0x111000
	s_addc_u32 s47, s3, 0
	s_and_b64 s[2:3], s[44:45], exec
	s_cselect_b32 s44, s46, s87
	s_cselect_b32 s45, s47, s21
	s_cmp_lt_u32 s33, 0x1000
	s_cbranch_scc0 .Lg2p8_0_hi
	s_add_u32 s2, s100, 0x0
	s_addc_u32 s3, s101, 0
	v_lshl_add_u64 v[240:241], s[2:3], 0, v[138:139]
	s_add_i32 m0, s33, 0x18000
	s_add_u32 s2, s2, 0x22200
	s_addc_u32 s3, s3, 0
	global_load_lds_dwordx4 v[240:241], off
	v_lshl_add_u64 v[242:243], s[2:3], 0, v[138:139]
	s_add_i32 m0, s33, 0x19000
	s_add_u32 s2, s2, 0x22200
	s_addc_u32 s3, s3, 0
	global_load_lds_dwordx4 v[242:243], off
	v_lshl_add_u64 v[240:241], s[2:3], 0, v[138:139]
	s_add_i32 m0, s33, 0x1a000
	s_add_u32 s2, s2, 0x22200
	s_addc_u32 s3, s3, 0
	global_load_lds_dwordx4 v[240:241], off
	v_lshl_add_u64 v[242:243], s[2:3], 0, v[138:139]
	s_add_i32 m0, s33, 0x1b000
	s_nop 0
	global_load_lds_dwordx4 v[242:243], off
	s_add_u32 s2, s98, 0x0
	s_addc_u32 s3, s99, 0
	v_lshl_add_u64 v[240:241], s[2:3], 0, v[136:137]
	s_add_i32 m0, s33, 0x8000
	s_add_u32 s2, s2, 0x101000
	s_addc_u32 s3, s3, 0
	global_load_lds_dwordx4 v[240:241], off
	v_lshl_add_u64 v[242:243], s[2:3], 0, v[136:137]
	s_add_i32 m0, s33, 0x9000
	s_add_u32 s2, s2, 0x101000
	s_addc_u32 s3, s3, 0
	global_load_lds_dwordx4 v[242:243], off
	v_lshl_add_u64 v[240:241], s[2:3], 0, v[136:137]
	s_add_i32 m0, s33, 0xa000
	s_add_u32 s2, s2, 0x101000
	s_addc_u32 s3, s3, 0
	global_load_lds_dwordx4 v[240:241], off
	v_lshl_add_u64 v[242:243], s[2:3], 0, v[136:137]
	s_add_i32 m0, s33, 0xb000
	s_nop 0
	global_load_lds_dwordx4 v[242:243], off
	s_branch .Lg2p8_0_done
.Lg2p8_0_hi:
	s_sub_u32 s2, s100, 0x21a00
	s_subb_u32 s3, s101, 0
	v_lshl_add_u64 v[240:241], s[2:3], 0, v[138:139]
	s_add_i32 m0, s33, 0x1b000
	s_add_u32 s2, s2, 0x22200
	s_addc_u32 s3, s3, 0
	global_load_lds_dwordx4 v[240:241], off
	v_lshl_add_u64 v[242:243], s[2:3], 0, v[138:139]
	s_add_i32 m0, s33, 0x1c000
	s_add_u32 s2, s2, 0x22200
	s_addc_u32 s3, s3, 0
	global_load_lds_dwordx4 v[242:243], off
	v_lshl_add_u64 v[240:241], s[2:3], 0, v[138:139]
	s_add_i32 m0, s33, 0x1d000
	s_add_u32 s2, s2, 0x22200
	s_addc_u32 s3, s3, 0
	global_load_lds_dwordx4 v[240:241], off
	v_lshl_add_u64 v[242:243], s[2:3], 0, v[138:139]
	s_add_i32 m0, s33, 0x1e000
	s_nop 0
	global_load_lds_dwordx4 v[242:243], off
	s_add_u32 s2, s98, 0x303000
	s_addc_u32 s3, s99, 0
	v_lshl_add_u64 v[240:241], s[2:3], 0, v[136:137]
	s_add_i32 m0, s33, 0xb000
	s_add_u32 s2, s2, 0x101000
	s_addc_u32 s3, s3, 0
	global_load_lds_dwordx4 v[240:241], off
	v_lshl_add_u64 v[242:243], s[2:3], 0, v[136:137]
	s_add_i32 m0, s33, 0xc000
	s_add_u32 s2, s2, 0x101000
	s_addc_u32 s3, s3, 0
	global_load_lds_dwordx4 v[242:243], off
	v_lshl_add_u64 v[240:241], s[2:3], 0, v[136:137]
	s_add_i32 m0, s33, 0xd000
	s_add_u32 s2, s2, 0x101000
	s_addc_u32 s3, s3, 0
	global_load_lds_dwordx4 v[240:241], off
	v_lshl_add_u64 v[242:243], s[2:3], 0, v[136:137]
	s_add_i32 m0, s33, 0xe000
	s_nop 0
	global_load_lds_dwordx4 v[242:243], off
.Lg2p8_0_done:
	s_add_i32 s2, 0, 0x10000
	v_add_u32_e32 v187, s2, v182
	ds_read_b128 v[128:131], v187
	ds_read_b128 v[132:135], v187 offset:256
	ds_read_b128 v[178:181], v187 offset:8192
	ds_read_b128 v[188:191], v187 offset:8448
	ds_read_b128 v[208:211], v185
	ds_read_b128 v[212:215], v185 offset:1024
	ds_read_b128 v[216:219], v185 offset:2048
	ds_read_b128 v[220:223], v185 offset:3072
	ds_read_b128 v[224:227], v185 offset:4096
	ds_read_b128 v[228:231], v185 offset:5120
	ds_read_b128 v[232:235], v185 offset:6144
	ds_read_b128 v[236:239], v185 offset:7168
	s_waitcnt lgkmcnt(0)
	s_barrier
	s_setprio 1
	s_add_i32 s2, 0, 0x14000
	v_add_u32_e32 v187, s2, v182
	v_mfma_f32_16x16x32_bf16 v[124:127], v[128:131], v[208:211], v[124:127]
	v_mfma_f32_16x16x32_bf16 v[120:123], v[132:135], v[208:211], v[120:123]
	ds_read_b128 v[192:195], v187
	v_mfma_f32_16x16x32_bf16 v[108:111], v[128:131], v[216:219], v[108:111]
	v_mfma_f32_16x16x32_bf16 v[104:107], v[132:135], v[216:219], v[104:107]
	ds_read_b128 v[196:199], v187 offset:256
	v_mfma_f32_16x16x32_bf16 v[92:95], v[128:131], v[224:227], v[92:95]
	v_mfma_f32_16x16x32_bf16 v[88:91], v[132:135], v[224:227], v[88:91]
	ds_read_b128 v[200:203], v187 offset:8192
	v_mfma_f32_16x16x32_bf16 v[76:79], v[128:131], v[232:235], v[76:79]
	v_mfma_f32_16x16x32_bf16 v[72:75], v[132:135], v[232:235], v[72:75]
	ds_read_b128 v[204:207], v187 offset:8448
	v_mfma_f32_16x16x32_bf16 v[124:127], v[178:181], v[212:215], v[124:127]
	v_mfma_f32_16x16x32_bf16 v[120:123], v[188:191], v[212:215], v[120:123]
	ds_read_b128 v[144:147], v185 offset:16384
	v_mfma_f32_16x16x32_bf16 v[108:111], v[178:181], v[220:223], v[108:111]
	v_mfma_f32_16x16x32_bf16 v[104:107], v[188:191], v[220:223], v[104:107]
	ds_read_b128 v[148:151], v185 offset:17408
	v_mfma_f32_16x16x32_bf16 v[92:95], v[178:181], v[228:231], v[92:95]
	v_mfma_f32_16x16x32_bf16 v[88:91], v[188:191], v[228:231], v[88:91]
	ds_read_b128 v[152:155], v185 offset:18432
	v_mfma_f32_16x16x32_bf16 v[76:79], v[178:181], v[236:239], v[76:79]
	v_mfma_f32_16x16x32_bf16 v[72:75], v[188:191], v[236:239], v[72:75]
	ds_read_b128 v[156:159], v185 offset:19456
	s_waitcnt lgkmcnt(4)
	v_mfma_f32_16x16x32_bf16 v[116:119], v[192:195], v[208:211], v[116:119]
	v_mfma_f32_16x16x32_bf16 v[112:115], v[196:199], v[208:211], v[112:115]
	ds_read_b128 v[160:163], v185 offset:20480
	v_mfma_f32_16x16x32_bf16 v[100:103], v[192:195], v[216:219], v[100:103]
	v_mfma_f32_16x16x32_bf16 v[96:99], v[196:199], v[216:219], v[96:99]
	ds_read_b128 v[164:167], v185 offset:21504
	v_mfma_f32_16x16x32_bf16 v[84:87], v[192:195], v[224:227], v[84:87]
	v_mfma_f32_16x16x32_bf16 v[80:83], v[196:199], v[224:227], v[80:83]
	ds_read_b128 v[168:171], v185 offset:22528
	v_mfma_f32_16x16x32_bf16 v[68:71], v[192:195], v[232:235], v[68:71]
	v_mfma_f32_16x16x32_bf16 v[64:67], v[196:199], v[232:235], v[64:67]
	ds_read_b128 v[172:175], v185 offset:23552
	v_mfma_f32_16x16x32_bf16 v[116:119], v[200:203], v[212:215], v[116:119]
	v_mfma_f32_16x16x32_bf16 v[112:115], v[204:207], v[212:215], v[112:115]
	v_mfma_f32_16x16x32_bf16 v[100:103], v[200:203], v[220:223], v[100:103]
	v_mfma_f32_16x16x32_bf16 v[96:99], v[204:207], v[220:223], v[96:99]
	v_mfma_f32_16x16x32_bf16 v[84:87], v[200:203], v[228:231], v[84:87]
	v_mfma_f32_16x16x32_bf16 v[80:83], v[204:207], v[228:231], v[80:83]
	v_mfma_f32_16x16x32_bf16 v[68:71], v[200:203], v[236:239], v[68:71]
	v_mfma_f32_16x16x32_bf16 v[64:67], v[204:207], v[236:239], v[64:67]
	s_waitcnt lgkmcnt(0)
	v_mfma_f32_16x16x32_bf16 v[60:63], v[128:131], v[144:147], v[60:63]
	v_mfma_f32_16x16x32_bf16 v[56:59], v[132:135], v[144:147], v[56:59]
	v_mfma_f32_16x16x32_bf16 v[44:47], v[128:131], v[152:155], v[44:47]
	v_mfma_f32_16x16x32_bf16 v[40:43], v[132:135], v[152:155], v[40:43]
	v_mfma_f32_16x16x32_bf16 v[28:31], v[128:131], v[160:163], v[28:31]
	v_mfma_f32_16x16x32_bf16 v[24:27], v[132:135], v[160:163], v[24:27]
	v_mfma_f32_16x16x32_bf16 v[12:15], v[128:131], v[168:171], v[12:15]
	v_mfma_f32_16x16x32_bf16 v[8:11], v[132:135], v[168:171], v[8:11]
	v_mfma_f32_16x16x32_bf16 v[60:63], v[178:181], v[148:151], v[60:63]
	v_mfma_f32_16x16x32_bf16 v[56:59], v[188:191], v[148:151], v[56:59]
	v_mfma_f32_16x16x32_bf16 v[44:47], v[178:181], v[156:159], v[44:47]
	v_mfma_f32_16x16x32_bf16 v[40:43], v[188:191], v[156:159], v[40:43]
	v_mfma_f32_16x16x32_bf16 v[28:31], v[178:181], v[164:167], v[28:31]
	v_mfma_f32_16x16x32_bf16 v[24:27], v[188:191], v[164:167], v[24:27]
	v_mfma_f32_16x16x32_bf16 v[12:15], v[178:181], v[172:175], v[12:15]
	v_mfma_f32_16x16x32_bf16 v[8:11], v[188:191], v[172:175], v[8:11]
	v_mfma_f32_16x16x32_bf16 v[52:55], v[192:195], v[144:147], v[52:55]
	v_mfma_f32_16x16x32_bf16 v[48:51], v[196:199], v[144:147], v[48:51]
	v_mfma_f32_16x16x32_bf16 v[36:39], v[192:195], v[152:155], v[36:39]
	v_mfma_f32_16x16x32_bf16 v[32:35], v[196:199], v[152:155], v[32:35]
	v_mfma_f32_16x16x32_bf16 v[20:23], v[192:195], v[160:163], v[20:23]
	v_mfma_f32_16x16x32_bf16 v[16:19], v[196:199], v[160:163], v[16:19]
	v_mfma_f32_16x16x32_bf16 v[4:7], v[192:195], v[168:171], v[4:7]
	v_mfma_f32_16x16x32_bf16 v[0:3], v[196:199], v[168:171], v[0:3]
	v_mfma_f32_16x16x32_bf16 v[52:55], v[200:203], v[148:151], v[52:55]
	v_mfma_f32_16x16x32_bf16 v[48:51], v[204:207], v[148:151], v[48:51]
	v_mfma_f32_16x16x32_bf16 v[36:39], v[200:203], v[156:159], v[36:39]
	v_mfma_f32_16x16x32_bf16 v[32:35], v[204:207], v[156:159], v[32:35]
	v_mfma_f32_16x16x32_bf16 v[20:23], v[200:203], v[164:167], v[20:23]
	v_mfma_f32_16x16x32_bf16 v[16:19], v[204:207], v[164:167], v[16:19]
	v_mfma_f32_16x16x32_bf16 v[4:7], v[200:203], v[172:175], v[4:7]
	v_mfma_f32_16x16x32_bf16 v[0:3], v[204:207], v[172:175], v[0:3]
	s_setprio 0
	s_waitcnt vmcnt(0)
	s_barrier
	s_cmp_lt_u32 s33, 0x1000
	s_cbranch_scc0 .Lg2p8_1_hi
	s_add_u32 s2, s44, 0x0
	s_addc_u32 s3, s45, 0
	v_lshl_add_u64 v[240:241], s[2:3], 0, v[138:139]
	s_add_i32 m0, s33, 0x10000
	s_add_u32 s2, s2, 0x22200
	s_addc_u32 s3, s3, 0
	global_load_lds_dwordx4 v[240:241], off
	v_lshl_add_u64 v[242:243], s[2:3], 0, v[138:139]
	s_add_i32 m0, s33, 0x11000
	s_add_u32 s2, s2, 0x22200
	s_addc_u32 s3, s3, 0
	global_load_lds_dwordx4 v[242:243], off
	v_lshl_add_u64 v[240:241], s[2:3], 0, v[138:139]
	s_add_i32 m0, s33, 0x12000
	s_add_u32 s2, s2, 0x22200
	s_addc_u32 s3, s3, 0
	global_load_lds_dwordx4 v[240:241], off
	v_lshl_add_u64 v[242:243], s[2:3], 0, v[138:139]
	s_add_i32 m0, s33, 0x13000
	s_nop 0
	global_load_lds_dwordx4 v[242:243], off
	s_add_u32 s2, s50, 0x0
	s_addc_u32 s3, s51, 0
	v_lshl_add_u64 v[240:241], s[2:3], 0, v[136:137]
	s_add_i32 m0, s33, 0x0
	s_add_u32 s2, s2, 0x101000
	s_addc_u32 s3, s3, 0
	global_load_lds_dwordx4 v[240:241], off
	v_lshl_add_u64 v[242:243], s[2:3], 0, v[136:137]
	s_add_i32 m0, s33, 0x1000
	s_add_u32 s2, s2, 0x101000
	s_addc_u32 s3, s3, 0
	global_load_lds_dwordx4 v[242:243], off
	v_lshl_add_u64 v[240:241], s[2:3], 0, v[136:137]
	s_add_i32 m0, s33, 0x2000
	s_add_u32 s2, s2, 0x101000
	s_addc_u32 s3, s3, 0
	global_load_lds_dwordx4 v[240:241], off
	v_lshl_add_u64 v[242:243], s[2:3], 0, v[136:137]
	s_add_i32 m0, s33, 0x3000
	s_nop 0
	global_load_lds_dwordx4 v[242:243], off
	s_branch .Lg2p8_1_done
.Lg2p8_1_hi:
	s_sub_u32 s2, s44, 0x21a00
	s_subb_u32 s3, s45, 0
	v_lshl_add_u64 v[240:241], s[2:3], 0, v[138:139]
	s_add_i32 m0, s33, 0x13000
	s_add_u32 s2, s2, 0x22200
	s_addc_u32 s3, s3, 0
	global_load_lds_dwordx4 v[240:241], off
	v_lshl_add_u64 v[242:243], s[2:3], 0, v[138:139]
	s_add_i32 m0, s33, 0x14000
	s_add_u32 s2, s2, 0x22200
	s_addc_u32 s3, s3, 0
	global_load_lds_dwordx4 v[242:243], off
	v_lshl_add_u64 v[240:241], s[2:3], 0, v[138:139]
	s_add_i32 m0, s33, 0x15000
	s_add_u32 s2, s2, 0x22200
	s_addc_u32 s3, s3, 0
	global_load_lds_dwordx4 v[240:241], off
	v_lshl_add_u64 v[242:243], s[2:3], 0, v[138:139]
	s_add_i32 m0, s33, 0x16000
	s_nop 0
	global_load_lds_dwordx4 v[242:243], off
	s_add_u32 s2, s50, 0x303000
	s_addc_u32 s3, s51, 0
	v_lshl_add_u64 v[240:241], s[2:3], 0, v[136:137]
	s_add_i32 m0, s33, 0x3000
	s_add_u32 s2, s2, 0x101000
	s_addc_u32 s3, s3, 0
	global_load_lds_dwordx4 v[240:241], off
	v_lshl_add_u64 v[242:243], s[2:3], 0, v[136:137]
	s_add_i32 m0, s33, 0x4000
	s_add_u32 s2, s2, 0x101000
	s_addc_u32 s3, s3, 0
	global_load_lds_dwordx4 v[242:243], off
	v_lshl_add_u64 v[240:241], s[2:3], 0, v[136:137]
	s_add_i32 m0, s33, 0x5000
	s_add_u32 s2, s2, 0x101000
	s_addc_u32 s3, s3, 0
	global_load_lds_dwordx4 v[240:241], off
	v_lshl_add_u64 v[242:243], s[2:3], 0, v[136:137]
	s_add_i32 m0, s33, 0x6000
	s_nop 0
	global_load_lds_dwordx4 v[242:243], off
.Lg2p8_1_done:
	s_add_i32 s2, 0, 0x18000
	v_add_u32_e32 v187, s2, v182
	ds_read_b128 v[128:131], v187
	ds_read_b128 v[132:135], v187 offset:256
	ds_read_b128 v[178:181], v187 offset:8192
	ds_read_b128 v[188:191], v187 offset:8448
	ds_read_b128 v[208:211], v185 offset:32768
	ds_read_b128 v[212:215], v185 offset:33792
	ds_read_b128 v[216:219], v185 offset:34816
	ds_read_b128 v[220:223], v185 offset:35840
	ds_read_b128 v[224:227], v185 offset:36864
	ds_read_b128 v[228:231], v185 offset:37888
	ds_read_b128 v[232:235], v185 offset:38912
	ds_read_b128 v[236:239], v185 offset:39936
	s_waitcnt lgkmcnt(0)
	s_barrier
	s_setprio 1
	s_add_i32 s2, 0, 0x1c000
	v_add_u32_e32 v187, s2, v182
	v_mfma_f32_16x16x32_bf16 v[124:127], v[128:131], v[208:211], v[124:127]
	v_mfma_f32_16x16x32_bf16 v[120:123], v[132:135], v[208:211], v[120:123]
	ds_read_b128 v[192:195], v187
	v_mfma_f32_16x16x32_bf16 v[108:111], v[128:131], v[216:219], v[108:111]
	v_mfma_f32_16x16x32_bf16 v[104:107], v[132:135], v[216:219], v[104:107]
	ds_read_b128 v[196:199], v187 offset:256
	v_mfma_f32_16x16x32_bf16 v[92:95], v[128:131], v[224:227], v[92:95]
	v_mfma_f32_16x16x32_bf16 v[88:91], v[132:135], v[224:227], v[88:91]
	ds_read_b128 v[200:203], v187 offset:8192
	v_mfma_f32_16x16x32_bf16 v[76:79], v[128:131], v[232:235], v[76:79]
	v_mfma_f32_16x16x32_bf16 v[72:75], v[132:135], v[232:235], v[72:75]
	ds_read_b128 v[204:207], v187 offset:8448
	v_mfma_f32_16x16x32_bf16 v[124:127], v[178:181], v[212:215], v[124:127]
	v_mfma_f32_16x16x32_bf16 v[120:123], v[188:191], v[212:215], v[120:123]
	ds_read_b128 v[144:147], v185 offset:49152
	v_mfma_f32_16x16x32_bf16 v[108:111], v[178:181], v[220:223], v[108:111]
	v_mfma_f32_16x16x32_bf16 v[104:107], v[188:191], v[220:223], v[104:107]
	ds_read_b128 v[148:151], v185 offset:50176
	v_mfma_f32_16x16x32_bf16 v[92:95], v[178:181], v[228:231], v[92:95]
	v_mfma_f32_16x16x32_bf16 v[88:91], v[188:191], v[228:231], v[88:91]
	ds_read_b128 v[152:155], v185 offset:51200
	v_mfma_f32_16x16x32_bf16 v[76:79], v[178:181], v[236:239], v[76:79]
	v_mfma_f32_16x16x32_bf16 v[72:75], v[188:191], v[236:239], v[72:75]
	ds_read_b128 v[156:159], v185 offset:52224
	s_waitcnt lgkmcnt(4)
	v_mfma_f32_16x16x32_bf16 v[116:119], v[192:195], v[208:211], v[116:119]
	v_mfma_f32_16x16x32_bf16 v[112:115], v[196:199], v[208:211], v[112:115]
	ds_read_b128 v[160:163], v185 offset:53248
	v_mfma_f32_16x16x32_bf16 v[100:103], v[192:195], v[216:219], v[100:103]
	v_mfma_f32_16x16x32_bf16 v[96:99], v[196:199], v[216:219], v[96:99]
	ds_read_b128 v[164:167], v185 offset:54272
	v_mfma_f32_16x16x32_bf16 v[84:87], v[192:195], v[224:227], v[84:87]
	v_mfma_f32_16x16x32_bf16 v[80:83], v[196:199], v[224:227], v[80:83]
	ds_read_b128 v[168:171], v185 offset:55296
	v_mfma_f32_16x16x32_bf16 v[68:71], v[192:195], v[232:235], v[68:71]
	v_mfma_f32_16x16x32_bf16 v[64:67], v[196:199], v[232:235], v[64:67]
	ds_read_b128 v[172:175], v185 offset:56320
	v_mfma_f32_16x16x32_bf16 v[116:119], v[200:203], v[212:215], v[116:119]
	v_mfma_f32_16x16x32_bf16 v[112:115], v[204:207], v[212:215], v[112:115]
	v_mfma_f32_16x16x32_bf16 v[100:103], v[200:203], v[220:223], v[100:103]
	v_mfma_f32_16x16x32_bf16 v[96:99], v[204:207], v[220:223], v[96:99]
	v_mfma_f32_16x16x32_bf16 v[84:87], v[200:203], v[228:231], v[84:87]
	v_mfma_f32_16x16x32_bf16 v[80:83], v[204:207], v[228:231], v[80:83]
	v_mfma_f32_16x16x32_bf16 v[68:71], v[200:203], v[236:239], v[68:71]
	v_mfma_f32_16x16x32_bf16 v[64:67], v[204:207], v[236:239], v[64:67]
	s_waitcnt lgkmcnt(0)
	v_mfma_f32_16x16x32_bf16 v[60:63], v[128:131], v[144:147], v[60:63]
	v_mfma_f32_16x16x32_bf16 v[56:59], v[132:135], v[144:147], v[56:59]
	v_mfma_f32_16x16x32_bf16 v[44:47], v[128:131], v[152:155], v[44:47]
	v_mfma_f32_16x16x32_bf16 v[40:43], v[132:135], v[152:155], v[40:43]
	v_mfma_f32_16x16x32_bf16 v[28:31], v[128:131], v[160:163], v[28:31]
	v_mfma_f32_16x16x32_bf16 v[24:27], v[132:135], v[160:163], v[24:27]
	v_mfma_f32_16x16x32_bf16 v[12:15], v[128:131], v[168:171], v[12:15]
	v_mfma_f32_16x16x32_bf16 v[8:11], v[132:135], v[168:171], v[8:11]
	v_mfma_f32_16x16x32_bf16 v[60:63], v[178:181], v[148:151], v[60:63]
	v_mfma_f32_16x16x32_bf16 v[56:59], v[188:191], v[148:151], v[56:59]
	v_mfma_f32_16x16x32_bf16 v[44:47], v[178:181], v[156:159], v[44:47]
	v_mfma_f32_16x16x32_bf16 v[40:43], v[188:191], v[156:159], v[40:43]
	v_mfma_f32_16x16x32_bf16 v[28:31], v[178:181], v[164:167], v[28:31]
	v_mfma_f32_16x16x32_bf16 v[24:27], v[188:191], v[164:167], v[24:27]
	v_mfma_f32_16x16x32_bf16 v[12:15], v[178:181], v[172:175], v[12:15]
	v_mfma_f32_16x16x32_bf16 v[8:11], v[188:191], v[172:175], v[8:11]
	v_mfma_f32_16x16x32_bf16 v[52:55], v[192:195], v[144:147], v[52:55]
	v_mfma_f32_16x16x32_bf16 v[48:51], v[196:199], v[144:147], v[48:51]
	v_mfma_f32_16x16x32_bf16 v[36:39], v[192:195], v[152:155], v[36:39]
	v_mfma_f32_16x16x32_bf16 v[32:35], v[196:199], v[152:155], v[32:35]
	v_mfma_f32_16x16x32_bf16 v[20:23], v[192:195], v[160:163], v[20:23]
	v_mfma_f32_16x16x32_bf16 v[16:19], v[196:199], v[160:163], v[16:19]
	v_mfma_f32_16x16x32_bf16 v[4:7], v[192:195], v[168:171], v[4:7]
	v_mfma_f32_16x16x32_bf16 v[0:3], v[196:199], v[168:171], v[0:3]
	v_mfma_f32_16x16x32_bf16 v[52:55], v[200:203], v[148:151], v[52:55]
	v_mfma_f32_16x16x32_bf16 v[48:51], v[204:207], v[148:151], v[48:51]
	v_mfma_f32_16x16x32_bf16 v[36:39], v[200:203], v[156:159], v[36:39]
	v_mfma_f32_16x16x32_bf16 v[32:35], v[204:207], v[156:159], v[32:35]
	v_mfma_f32_16x16x32_bf16 v[20:23], v[200:203], v[164:167], v[20:23]
	v_mfma_f32_16x16x32_bf16 v[16:19], v[204:207], v[164:167], v[16:19]
	v_mfma_f32_16x16x32_bf16 v[4:7], v[200:203], v[172:175], v[4:7]
	v_mfma_f32_16x16x32_bf16 v[0:3], v[204:207], v[172:175], v[0:3]
	s_setprio 0
	s_waitcnt vmcnt(0)
	s_barrier
	s_add_i32 s2, s88, 2
	s_cmpk_gt_u32 s88, 0xfd
	s_cbranch_scc1 .LBB0_939
	s_mov_b32 s88, s2
	s_branch .LBB0_904

.LBB0_941:
	s_lshr_b32 s2, s31, 12
	s_lshl_b32 s2, s2, 6
	v_bfe_u32 v246, v184, 2, 4
	v_or_b32_e32 v246, s2, v246
	s_movk_i32 s2, 0x2080
	v_mov_b32_e32 v251, 0
	v_mov_b32_e32 v250, v246
	v_lshlrev_b64 v[144:145], 14, v[250:251]
	v_mad_i64_i32 v[160:161], vcc, v250, s2, 0
	v_add_u32_e32 v250, 16, v246
	v_lshlrev_b64 v[146:147], 14, v[250:251]
	v_mad_i64_i32 v[162:163], vcc, v250, s2, 0
	v_add_u32_e32 v250, 32, v246
	v_lshlrev_b64 v[148:149], 14, v[250:251]
	v_mad_i64_i32 v[164:165], vcc, v250, s2, 0
	v_add_u32_e32 v250, 48, v246
	v_lshlrev_b64 v[150:151], 14, v[250:251]
	v_mad_i64_i32 v[166:167], vcc, v250, s2, 0
	v_add_u32_e32 v250, 0x80, v246
	v_lshlrev_b64 v[152:153], 14, v[250:251]
	v_mad_i64_i32 v[168:169], vcc, v250, s2, 0
	v_add_u32_e32 v250, 0x90, v246
	v_lshlrev_b64 v[154:155], 14, v[250:251]
	v_mad_i64_i32 v[170:171], vcc, v250, s2, 0
	v_add_u32_e32 v250, 0xa0, v246
	v_lshlrev_b64 v[156:157], 14, v[250:251]
	v_mad_i64_i32 v[172:173], vcc, v250, s2, 0
	v_add_u32_e32 v250, 0xb0, v246
	v_lshlrev_b64 v[158:159], 14, v[250:251]
	v_mad_i64_i32 v[174:175], vcc, v250, s2, 0
	s_lshl_b32 s2, s86, 8
	s_add_i32 s3, s2, 0xffffe000
	s_ashr_i32 s3, s3, 10
	s_add_i32 s3, s3, 1
	s_cmp_gt_i32 s86, 31
	s_cselect_b32 s21, s3, 0
	s_ashr_i32 s3, s2, 31
	s_lshl_b64 s[26:27], s[2:3], 14
	s_mul_hi_i32 s3, s21, 0x18000
	s_mul_i32 s21, s21, 0x18000
	s_add_u32 s34, s76, s21
	s_addc_u32 s35, s77, s3
	s_mul_i32 s3, s86, 0x208000
	v_lshl_or_b32 v128, s30, 8, v183
	s_mul_hi_i32 s21, s2, 0x2080
	s_add_u32 s2, s96, s3
	v_ashrrev_i32_e32 v129, 31, v128
	s_addc_u32 s3, s97, s21
	v_lshl_add_u64 v[180:181], v[128:129], 1, s[2:3]
	v_lshl_add_u64 v[196:197], v[180:181], 0, v[160:161]
	global_load_dwordx4 v[188:191], v[196:197], off nt
	v_lshlrev_b64 v[178:179], 2, v[128:129]
	v_lshl_add_u64 v[192:193], s[34:35], 0, v[178:179]
	global_load_dwordx4 v[132:135], v[192:193], off
	global_load_dwordx4 v[128:131], v[192:193], off offset:16
	ds_bpermute_b32 v194, v184, v124
	ds_bpermute_b32 v195, v184, v125
	ds_bpermute_b32 v198, v184, v126
	ds_bpermute_b32 v199, v184, v127
	ds_bpermute_b32 v200, v184, v120
	ds_bpermute_b32 v201, v184, v121
	ds_bpermute_b32 v202, v184, v122
	ds_bpermute_b32 v203, v184, v123
	s_add_u32 s2, s48, s26
	s_addc_u32 s3, s49, s27
	global_load_dwordx4 v[120:123], v[192:193], off offset:528
	global_load_dwordx4 v[124:127], v[192:193], off offset:512
	v_lshl_add_u64 v[178:179], s[2:3], 0, v[178:179]
	v_lshl_add_u64 v[204:205], v[178:179], 0, v[144:145]
	ds_bpermute_b32 v116, v184, v116
	ds_bpermute_b32 v117, v184, v117
	ds_bpermute_b32 v118, v184, v118
	ds_bpermute_b32 v119, v184, v119
	ds_bpermute_b32 v108, v184, v108
	ds_bpermute_b32 v109, v184, v109
	ds_bpermute_b32 v110, v184, v110
	ds_bpermute_b32 v111, v184, v111
	ds_bpermute_b32 v100, v184, v100
	ds_bpermute_b32 v101, v184, v101
	ds_bpermute_b32 v102, v184, v102
	ds_bpermute_b32 v103, v184, v103
	ds_bpermute_b32 v92, v184, v92
	ds_bpermute_b32 v93, v184, v93
	ds_bpermute_b32 v94, v184, v94
	ds_bpermute_b32 v95, v184, v95
	ds_bpermute_b32 v84, v184, v84
	ds_bpermute_b32 v85, v184, v85
	ds_bpermute_b32 v86, v184, v86
	ds_bpermute_b32 v87, v184, v87
	ds_bpermute_b32 v76, v184, v76
	ds_bpermute_b32 v77, v184, v77
	ds_bpermute_b32 v78, v184, v78
	ds_bpermute_b32 v79, v184, v79
	ds_bpermute_b32 v68, v184, v68
	ds_bpermute_b32 v69, v184, v69
	ds_bpermute_b32 v70, v184, v70
	ds_bpermute_b32 v71, v184, v71
	ds_bpermute_b32 v60, v184, v60
	ds_bpermute_b32 v61, v184, v61
	ds_bpermute_b32 v62, v184, v62
	ds_bpermute_b32 v63, v184, v63
	ds_bpermute_b32 v52, v184, v52
	ds_bpermute_b32 v53, v184, v53
	ds_bpermute_b32 v54, v184, v54
	ds_bpermute_b32 v55, v184, v55
	ds_bpermute_b32 v44, v184, v44
	ds_bpermute_b32 v45, v184, v45
	ds_bpermute_b32 v46, v184, v46
	ds_bpermute_b32 v47, v184, v47
	ds_bpermute_b32 v36, v184, v36
	ds_bpermute_b32 v37, v184, v37
	ds_bpermute_b32 v38, v184, v38
	ds_bpermute_b32 v39, v184, v39
	ds_bpermute_b32 v28, v184, v28
	ds_bpermute_b32 v29, v184, v29
	ds_bpermute_b32 v30, v184, v30
	ds_bpermute_b32 v31, v184, v31
	ds_bpermute_b32 v20, v184, v20
	ds_bpermute_b32 v21, v184, v21
	ds_bpermute_b32 v22, v184, v22
	ds_bpermute_b32 v23, v184, v23
	ds_bpermute_b32 v12, v184, v12
	ds_bpermute_b32 v13, v184, v13
	ds_bpermute_b32 v14, v184, v14
	ds_bpermute_b32 v15, v184, v15
	ds_bpermute_b32 v4, v184, v4
	ds_bpermute_b32 v5, v184, v5
	ds_bpermute_b32 v6, v184, v6
	ds_bpermute_b32 v7, v184, v7
	s_andn2_b64 vcc, exec, s[28:29]
	s_mov_b64 s[2:3], -1
	s_waitcnt vmcnt(0)
	v_lshlrev_b32_e32 v192, 16, v188
	v_and_b32_e32 v193, 0xffff0000, v188
	v_lshlrev_b32_e32 v206, 16, v189
	v_and_b32_e32 v207, 0xffff0000, v189
	v_lshlrev_b32_e32 v208, 16, v190
	v_and_b32_e32 v209, 0xffff0000, v190
	v_lshlrev_b32_e32 v210, 16, v191
	v_and_b32_e32 v211, 0xffff0000, v191
	s_waitcnt lgkmcnt(14)
	v_pk_fma_f32 v[188:189], v[132:133], v[194:195], v[192:193]
	v_pk_fma_f32 v[190:191], v[134:135], v[198:199], v[206:207]
	v_pk_fma_f32 v[192:193], v[128:129], v[200:201], v[208:209]
	v_pk_fma_f32 v[194:195], v[130:131], v[202:203], v[210:211]
	global_store_dwordx4 v[204:205], v[188:191], off
	global_store_dwordx4 v[204:205], v[192:195], off offset:16
	global_load_dwordx4 v[188:191], v[196:197], off offset:256 nt
	ds_bpermute_b32 v192, v184, v112
	ds_bpermute_b32 v193, v184, v113
	ds_bpermute_b32 v194, v184, v114
	ds_bpermute_b32 v195, v184, v115
	v_lshl_add_u64 v[196:197], v[180:181], 0, v[162:163]
	s_waitcnt vmcnt(0)
	v_lshlrev_b32_e32 v112, 16, v188
	v_and_b32_e32 v113, 0xffff0000, v188
	v_lshlrev_b32_e32 v114, 16, v189
	v_and_b32_e32 v115, 0xffff0000, v189
	v_lshlrev_b32_e32 v188, 16, v190
	v_and_b32_e32 v189, 0xffff0000, v190
	v_lshlrev_b32_e32 v190, 16, v191
	v_and_b32_e32 v191, 0xffff0000, v191
	v_pk_fma_f32 v[114:115], v[126:127], v[118:119], v[114:115]
	v_pk_fma_f32 v[112:113], v[124:125], v[116:117], v[112:113]
	s_waitcnt lgkmcnt(0)
	v_pk_fma_f32 v[118:119], v[122:123], v[194:195], v[190:191]
	v_pk_fma_f32 v[116:117], v[120:121], v[192:193], v[188:189]
	global_store_dwordx4 v[204:205], v[112:115], off offset:512
	global_store_dwordx4 v[204:205], v[116:119], off offset:528
	global_load_dwordx4 v[112:115], v[196:197], off nt
	ds_bpermute_b32 v116, v184, v104
	ds_bpermute_b32 v117, v184, v105
	ds_bpermute_b32 v118, v184, v106
	ds_bpermute_b32 v119, v184, v107
	v_lshl_add_u64 v[188:189], v[178:179], 0, v[146:147]
	s_waitcnt vmcnt(0)
	v_lshlrev_b32_e32 v104, 16, v112
	v_and_b32_e32 v105, 0xffff0000, v112
	v_lshlrev_b32_e32 v106, 16, v113
	v_and_b32_e32 v107, 0xffff0000, v113
	v_lshlrev_b32_e32 v112, 16, v114
	v_and_b32_e32 v113, 0xffff0000, v114
	v_lshlrev_b32_e32 v114, 16, v115
	v_and_b32_e32 v115, 0xffff0000, v115
	v_pk_fma_f32 v[106:107], v[134:135], v[110:111], v[106:107]
	v_pk_fma_f32 v[104:105], v[132:133], v[108:109], v[104:105]
	s_waitcnt lgkmcnt(0)
	v_pk_fma_f32 v[110:111], v[130:131], v[118:119], v[114:115]
	v_pk_fma_f32 v[108:109], v[128:129], v[116:117], v[112:113]
	global_store_dwordx4 v[188:189], v[104:107], off
	global_store_dwordx4 v[188:189], v[108:111], off offset:16
	global_load_dwordx4 v[104:107], v[196:197], off offset:256 nt
	ds_bpermute_b32 v108, v184, v96
	ds_bpermute_b32 v109, v184, v97
	ds_bpermute_b32 v110, v184, v98
	ds_bpermute_b32 v111, v184, v99
	v_lshl_add_u64 v[112:113], v[180:181], 0, v[164:165]
	s_waitcnt vmcnt(0)
	v_lshlrev_b32_e32 v96, 16, v104
	v_and_b32_e32 v97, 0xffff0000, v104
	v_lshlrev_b32_e32 v98, 16, v105
	v_and_b32_e32 v99, 0xffff0000, v105
	v_lshlrev_b32_e32 v104, 16, v106
	v_and_b32_e32 v105, 0xffff0000, v106
	v_lshlrev_b32_e32 v106, 16, v107
	v_and_b32_e32 v107, 0xffff0000, v107
	v_pk_fma_f32 v[98:99], v[126:127], v[102:103], v[98:99]
	v_pk_fma_f32 v[96:97], v[124:125], v[100:101], v[96:97]
	s_waitcnt lgkmcnt(0)
	v_pk_fma_f32 v[102:103], v[122:123], v[110:111], v[106:107]
	v_pk_fma_f32 v[100:101], v[120:121], v[108:109], v[104:105]
	global_store_dwordx4 v[188:189], v[96:99], off offset:512
	global_store_dwordx4 v[188:189], v[100:103], off offset:528
	global_load_dwordx4 v[96:99], v[112:113], off nt
	ds_bpermute_b32 v100, v184, v88
	ds_bpermute_b32 v101, v184, v89
	ds_bpermute_b32 v102, v184, v90
	ds_bpermute_b32 v103, v184, v91
	v_lshl_add_u64 v[104:105], v[178:179], 0, v[148:149]
	s_waitcnt vmcnt(0)
	v_lshlrev_b32_e32 v88, 16, v96
	v_and_b32_e32 v89, 0xffff0000, v96
	v_lshlrev_b32_e32 v90, 16, v97
	v_and_b32_e32 v91, 0xffff0000, v97
	v_lshlrev_b32_e32 v96, 16, v98
	v_and_b32_e32 v97, 0xffff0000, v98
	v_lshlrev_b32_e32 v98, 16, v99
	v_and_b32_e32 v99, 0xffff0000, v99
	v_pk_fma_f32 v[90:91], v[134:135], v[94:95], v[90:91]
	v_pk_fma_f32 v[88:89], v[132:133], v[92:93], v[88:89]
	s_waitcnt lgkmcnt(0)
	v_pk_fma_f32 v[94:95], v[130:131], v[102:103], v[98:99]
	v_pk_fma_f32 v[92:93], v[128:129], v[100:101], v[96:97]
	global_store_dwordx4 v[104:105], v[88:91], off
	global_store_dwordx4 v[104:105], v[92:95], off offset:16
	global_load_dwordx4 v[88:91], v[112:113], off offset:256 nt
	ds_bpermute_b32 v92, v184, v80
	ds_bpermute_b32 v93, v184, v81
	ds_bpermute_b32 v94, v184, v82
	ds_bpermute_b32 v95, v184, v83
	v_lshl_add_u64 v[96:97], v[180:181], 0, v[166:167]
	s_waitcnt vmcnt(0)
	v_lshlrev_b32_e32 v80, 16, v88
	v_and_b32_e32 v81, 0xffff0000, v88
	v_lshlrev_b32_e32 v82, 16, v89
	v_and_b32_e32 v83, 0xffff0000, v89
	v_lshlrev_b32_e32 v88, 16, v90
	v_and_b32_e32 v89, 0xffff0000, v90
	v_lshlrev_b32_e32 v90, 16, v91
	v_and_b32_e32 v91, 0xffff0000, v91
	v_pk_fma_f32 v[82:83], v[126:127], v[86:87], v[82:83]
	v_pk_fma_f32 v[80:81], v[124:125], v[84:85], v[80:81]
	s_waitcnt lgkmcnt(0)
	v_pk_fma_f32 v[86:87], v[122:123], v[94:95], v[90:91]
	v_pk_fma_f32 v[84:85], v[120:121], v[92:93], v[88:89]
	global_store_dwordx4 v[104:105], v[80:83], off offset:512
	global_store_dwordx4 v[104:105], v[84:87], off offset:528
	global_load_dwordx4 v[80:83], v[96:97], off nt
	ds_bpermute_b32 v84, v184, v72
	ds_bpermute_b32 v85, v184, v73
	ds_bpermute_b32 v86, v184, v74
	ds_bpermute_b32 v87, v184, v75
	v_lshl_add_u64 v[88:89], v[178:179], 0, v[150:151]
	s_waitcnt vmcnt(0)
	v_lshlrev_b32_e32 v72, 16, v80
	v_and_b32_e32 v73, 0xffff0000, v80
	v_lshlrev_b32_e32 v74, 16, v81
	v_and_b32_e32 v75, 0xffff0000, v81
	v_lshlrev_b32_e32 v80, 16, v82
	v_and_b32_e32 v81, 0xffff0000, v82
	v_lshlrev_b32_e32 v82, 16, v83
	v_and_b32_e32 v83, 0xffff0000, v83
	v_pk_fma_f32 v[74:75], v[134:135], v[78:79], v[74:75]
	v_pk_fma_f32 v[72:73], v[132:133], v[76:77], v[72:73]
	s_waitcnt lgkmcnt(0)
	v_pk_fma_f32 v[78:79], v[130:131], v[86:87], v[82:83]
	v_pk_fma_f32 v[76:77], v[128:129], v[84:85], v[80:81]
	global_store_dwordx4 v[88:89], v[72:75], off
	global_store_dwordx4 v[88:89], v[76:79], off offset:16
	global_load_dwordx4 v[72:75], v[96:97], off offset:256 nt
	ds_bpermute_b32 v76, v184, v64
	ds_bpermute_b32 v77, v184, v65
	ds_bpermute_b32 v78, v184, v66
	ds_bpermute_b32 v79, v184, v67
	v_lshl_add_u64 v[80:81], v[180:181], 0, v[168:169]
	s_waitcnt vmcnt(0)
	v_lshlrev_b32_e32 v64, 16, v72
	v_and_b32_e32 v65, 0xffff0000, v72
	v_lshlrev_b32_e32 v66, 16, v73
	v_and_b32_e32 v67, 0xffff0000, v73
	v_lshlrev_b32_e32 v72, 16, v74
	v_and_b32_e32 v73, 0xffff0000, v74
	v_lshlrev_b32_e32 v74, 16, v75
	v_and_b32_e32 v75, 0xffff0000, v75
	v_pk_fma_f32 v[66:67], v[126:127], v[70:71], v[66:67]
	v_pk_fma_f32 v[64:65], v[124:125], v[68:69], v[64:65]
	s_waitcnt lgkmcnt(0)
	v_pk_fma_f32 v[70:71], v[122:123], v[78:79], v[74:75]
	v_pk_fma_f32 v[68:69], v[120:121], v[76:77], v[72:73]
	global_store_dwordx4 v[88:89], v[64:67], off offset:512
	global_store_dwordx4 v[88:89], v[68:71], off offset:528
	global_load_dwordx4 v[64:67], v[80:81], off nt
	ds_bpermute_b32 v68, v184, v56
	ds_bpermute_b32 v69, v184, v57
	ds_bpermute_b32 v70, v184, v58
	ds_bpermute_b32 v71, v184, v59
	v_lshl_add_u64 v[72:73], v[178:179], 0, v[152:153]
	s_waitcnt vmcnt(0)
	v_lshlrev_b32_e32 v56, 16, v64
	v_and_b32_e32 v57, 0xffff0000, v64
	v_lshlrev_b32_e32 v58, 16, v65
	v_and_b32_e32 v59, 0xffff0000, v65
	v_lshlrev_b32_e32 v64, 16, v66
	v_and_b32_e32 v65, 0xffff0000, v66
	v_lshlrev_b32_e32 v66, 16, v67
	v_and_b32_e32 v67, 0xffff0000, v67
	v_pk_fma_f32 v[58:59], v[134:135], v[62:63], v[58:59]
	v_pk_fma_f32 v[56:57], v[132:133], v[60:61], v[56:57]
	s_waitcnt lgkmcnt(0)
	v_pk_fma_f32 v[62:63], v[130:131], v[70:71], v[66:67]
	v_pk_fma_f32 v[60:61], v[128:129], v[68:69], v[64:65]
	global_store_dwordx4 v[72:73], v[56:59], off
	global_store_dwordx4 v[72:73], v[60:63], off offset:16
	global_load_dwordx4 v[56:59], v[80:81], off offset:256 nt
	ds_bpermute_b32 v60, v184, v48
	ds_bpermute_b32 v61, v184, v49
	ds_bpermute_b32 v62, v184, v50
	ds_bpermute_b32 v63, v184, v51
	v_lshl_add_u64 v[64:65], v[180:181], 0, v[170:171]
	s_waitcnt vmcnt(0)
	v_lshlrev_b32_e32 v48, 16, v56
	v_and_b32_e32 v49, 0xffff0000, v56
	v_lshlrev_b32_e32 v50, 16, v57
	v_and_b32_e32 v51, 0xffff0000, v57
	v_lshlrev_b32_e32 v56, 16, v58
	v_and_b32_e32 v57, 0xffff0000, v58
	v_lshlrev_b32_e32 v58, 16, v59
	v_and_b32_e32 v59, 0xffff0000, v59
	v_pk_fma_f32 v[50:51], v[126:127], v[54:55], v[50:51]
	v_pk_fma_f32 v[48:49], v[124:125], v[52:53], v[48:49]
	s_waitcnt lgkmcnt(0)
	v_pk_fma_f32 v[54:55], v[122:123], v[62:63], v[58:59]
	v_pk_fma_f32 v[52:53], v[120:121], v[60:61], v[56:57]
	global_store_dwordx4 v[72:73], v[48:51], off offset:512
	global_store_dwordx4 v[72:73], v[52:55], off offset:528
	global_load_dwordx4 v[48:51], v[64:65], off nt
	ds_bpermute_b32 v52, v184, v40
	ds_bpermute_b32 v53, v184, v41
	ds_bpermute_b32 v54, v184, v42
	ds_bpermute_b32 v55, v184, v43
	v_lshl_add_u64 v[56:57], v[178:179], 0, v[154:155]
	s_waitcnt vmcnt(0)
	v_lshlrev_b32_e32 v40, 16, v48
	v_and_b32_e32 v41, 0xffff0000, v48
	v_lshlrev_b32_e32 v42, 16, v49
	v_and_b32_e32 v43, 0xffff0000, v49
	v_lshlrev_b32_e32 v48, 16, v50
	v_and_b32_e32 v49, 0xffff0000, v50
	v_lshlrev_b32_e32 v50, 16, v51
	v_and_b32_e32 v51, 0xffff0000, v51
	v_pk_fma_f32 v[42:43], v[134:135], v[46:47], v[42:43]
	v_pk_fma_f32 v[40:41], v[132:133], v[44:45], v[40:41]
	s_waitcnt lgkmcnt(0)
	v_pk_fma_f32 v[46:47], v[130:131], v[54:55], v[50:51]
	v_pk_fma_f32 v[44:45], v[128:129], v[52:53], v[48:49]
	global_store_dwordx4 v[56:57], v[40:43], off
	global_store_dwordx4 v[56:57], v[44:47], off offset:16
	global_load_dwordx4 v[40:43], v[64:65], off offset:256 nt
	ds_bpermute_b32 v44, v184, v32
	ds_bpermute_b32 v45, v184, v33
	ds_bpermute_b32 v46, v184, v34
	ds_bpermute_b32 v47, v184, v35
	v_lshl_add_u64 v[48:49], v[180:181], 0, v[172:173]
	s_waitcnt vmcnt(0)
	v_lshlrev_b32_e32 v32, 16, v40
	v_and_b32_e32 v33, 0xffff0000, v40
	v_lshlrev_b32_e32 v34, 16, v41
	v_and_b32_e32 v35, 0xffff0000, v41
	v_lshlrev_b32_e32 v40, 16, v42
	v_and_b32_e32 v41, 0xffff0000, v42
	v_lshlrev_b32_e32 v42, 16, v43
	v_and_b32_e32 v43, 0xffff0000, v43
	v_pk_fma_f32 v[34:35], v[126:127], v[38:39], v[34:35]
	v_pk_fma_f32 v[32:33], v[124:125], v[36:37], v[32:33]
	s_waitcnt lgkmcnt(0)
	v_pk_fma_f32 v[38:39], v[122:123], v[46:47], v[42:43]
	v_pk_fma_f32 v[36:37], v[120:121], v[44:45], v[40:41]
	global_store_dwordx4 v[56:57], v[32:35], off offset:512
	global_store_dwordx4 v[56:57], v[36:39], off offset:528
	global_load_dwordx4 v[32:35], v[48:49], off nt
	ds_bpermute_b32 v36, v184, v24
	ds_bpermute_b32 v37, v184, v25
	ds_bpermute_b32 v38, v184, v26
	ds_bpermute_b32 v39, v184, v27
	v_lshl_add_u64 v[40:41], v[178:179], 0, v[156:157]
	s_waitcnt vmcnt(0)
	v_lshlrev_b32_e32 v24, 16, v32
	v_and_b32_e32 v25, 0xffff0000, v32
	v_lshlrev_b32_e32 v26, 16, v33
	v_and_b32_e32 v27, 0xffff0000, v33
	v_lshlrev_b32_e32 v32, 16, v34
	v_and_b32_e32 v33, 0xffff0000, v34
	v_lshlrev_b32_e32 v34, 16, v35
	v_and_b32_e32 v35, 0xffff0000, v35
	v_pk_fma_f32 v[26:27], v[134:135], v[30:31], v[26:27]
	v_pk_fma_f32 v[24:25], v[132:133], v[28:29], v[24:25]
	s_waitcnt lgkmcnt(0)
	v_pk_fma_f32 v[30:31], v[130:131], v[38:39], v[34:35]
	v_pk_fma_f32 v[28:29], v[128:129], v[36:37], v[32:33]
	global_store_dwordx4 v[40:41], v[24:27], off
	global_store_dwordx4 v[40:41], v[28:31], off offset:16
	global_load_dwordx4 v[24:27], v[48:49], off offset:256 nt
	ds_bpermute_b32 v28, v184, v16
	ds_bpermute_b32 v29, v184, v17
	ds_bpermute_b32 v30, v184, v18
	ds_bpermute_b32 v31, v184, v19
	v_lshl_add_u64 v[32:33], v[180:181], 0, v[174:175]
	s_waitcnt vmcnt(0)
	v_lshlrev_b32_e32 v16, 16, v24
	v_and_b32_e32 v17, 0xffff0000, v24
	v_lshlrev_b32_e32 v18, 16, v25
	v_and_b32_e32 v19, 0xffff0000, v25
	v_lshlrev_b32_e32 v24, 16, v26
	v_and_b32_e32 v25, 0xffff0000, v26
	v_lshlrev_b32_e32 v26, 16, v27
	v_and_b32_e32 v27, 0xffff0000, v27
	v_pk_fma_f32 v[18:19], v[126:127], v[22:23], v[18:19]
	v_pk_fma_f32 v[16:17], v[124:125], v[20:21], v[16:17]
	s_waitcnt lgkmcnt(0)
	v_pk_fma_f32 v[22:23], v[122:123], v[30:31], v[26:27]
	v_pk_fma_f32 v[20:21], v[120:121], v[28:29], v[24:25]
	global_store_dwordx4 v[40:41], v[16:19], off offset:512
	global_store_dwordx4 v[40:41], v[20:23], off offset:528
	global_load_dwordx4 v[16:19], v[32:33], off nt
	ds_bpermute_b32 v20, v184, v8
	ds_bpermute_b32 v21, v184, v9
	ds_bpermute_b32 v22, v184, v10
	ds_bpermute_b32 v23, v184, v11
	v_lshl_add_u64 v[24:25], v[178:179], 0, v[158:159]
	s_waitcnt vmcnt(0)
	v_lshlrev_b32_e32 v8, 16, v16
	v_and_b32_e32 v9, 0xffff0000, v16
	v_lshlrev_b32_e32 v10, 16, v17
	v_and_b32_e32 v11, 0xffff0000, v17
	v_lshlrev_b32_e32 v16, 16, v18
	v_and_b32_e32 v17, 0xffff0000, v18
	v_lshlrev_b32_e32 v18, 16, v19
	v_and_b32_e32 v19, 0xffff0000, v19
	v_pk_fma_f32 v[10:11], v[134:135], v[14:15], v[10:11]
	v_pk_fma_f32 v[8:9], v[132:133], v[12:13], v[8:9]
	s_waitcnt lgkmcnt(0)
	v_pk_fma_f32 v[14:15], v[130:131], v[22:23], v[18:19]
	v_pk_fma_f32 v[12:13], v[128:129], v[20:21], v[16:17]
	global_store_dwordx4 v[24:25], v[8:11], off
	global_store_dwordx4 v[24:25], v[12:15], off offset:16
	global_load_dwordx4 v[8:11], v[32:33], off offset:256 nt
	ds_bpermute_b32 v12, v184, v0
	ds_bpermute_b32 v13, v184, v1
	ds_bpermute_b32 v14, v184, v2
	ds_bpermute_b32 v15, v184, v3
	s_waitcnt vmcnt(0)
	v_lshlrev_b32_e32 v0, 16, v8
	v_and_b32_e32 v1, 0xffff0000, v8
	v_lshlrev_b32_e32 v2, 16, v9
	v_and_b32_e32 v3, 0xffff0000, v9
	v_lshlrev_b32_e32 v8, 16, v10
	v_and_b32_e32 v9, 0xffff0000, v10
	v_lshlrev_b32_e32 v10, 16, v11
	v_and_b32_e32 v11, 0xffff0000, v11
	v_pk_fma_f32 v[2:3], v[126:127], v[6:7], v[2:3]
	v_pk_fma_f32 v[0:1], v[124:125], v[4:5], v[0:1]
	s_waitcnt lgkmcnt(0)
	v_pk_fma_f32 v[6:7], v[122:123], v[14:15], v[10:11]
	v_pk_fma_f32 v[4:5], v[120:121], v[12:13], v[8:9]
	global_store_dwordx4 v[24:25], v[0:3], off offset:512
	global_store_dwordx4 v[24:25], v[4:7], off offset:528
	s_cbranch_vccnz .LBB0_896
	s_andn2_b64 vcc, exec, s[10:11]
	s_cbranch_vccnz .LBB0_895
	s_barrier
	s_branch .LBB0_895
